# back-edge rotation: loop-carried SALU moved before the loop-back barrier in all 4 GEMM loops
# baseline (speedup 1.0000x reference)
.LBB0_101:
	ds_read_b128 v[142:145], v161
	ds_read_b128 v[146:149], v234
	ds_read_b128 v[150:153], v161 offset:2048
	ds_read_b128 v[154:157], v234 offset:2048
	ds_read_b128 v[164:167], v162
	ds_read_b128 v[168:171], v235
	ds_read_b128 v[172:175], v162 offset:2048
	ds_read_b128 v[176:179], v235 offset:2048
	s_add_u32 s48, s46, 0xfff00080
	s_addc_u32 s49, s47, -1
	s_cmp_eq_u32 s77, 60
	s_cselect_b32 s51, s5, s49
	s_cselect_b32 s50, s29, s48
	s_cselect_b32 s49, s27, s76
	s_cselect_b32 s48, s74, s75
	v_lshl_add_u64 v[214:215], s[46:47], 0, v[134:135]
	s_add_i32 m0, s19, 0xc000
	ds_read_b128 v[180:183], v163
	ds_read_b128 v[184:187], v232
	ds_read_b128 v[188:191], v163 offset:2048
	ds_read_b128 v[192:195], v232 offset:2048
	ds_read_b128 v[196:199], v163 offset:4096
	ds_read_b128 v[200:203], v232 offset:4096
	ds_read_b128 v[204:207], v163 offset:6144
	ds_read_b128 v[208:211], v232 offset:6144
	global_load_lds_dwordx4 v[214:215], off
	v_lshl_add_u64 v[214:215], s[46:47], 0, v[136:137]
	s_add_i32 m0, s19, 0xe000
	s_nop 0
	global_load_lds_dwordx4 v[214:215], off
	s_waitcnt vmcnt(8)
	s_waitcnt lgkmcnt(0)
	s_barrier
	s_setprio 1
	s_waitcnt lgkmcnt(0)
	v_mfma_f32_16x16x32_bf16 v[124:127], v[142:145], v[180:183], v[124:127]
	v_mfma_f32_16x16x32_bf16 v[120:123], v[150:153], v[180:183], v[120:123]
	v_mfma_f32_16x16x32_bf16 v[116:119], v[142:145], v[188:191], v[116:119]
	v_mfma_f32_16x16x32_bf16 v[112:115], v[150:153], v[188:191], v[112:115]
	v_mfma_f32_16x16x32_bf16 v[100:103], v[142:145], v[196:199], v[100:103]
	v_mfma_f32_16x16x32_bf16 v[96:99], v[150:153], v[196:199], v[96:99]
	v_mfma_f32_16x16x32_bf16 v[84:87], v[142:145], v[204:207], v[84:87]
	v_mfma_f32_16x16x32_bf16 v[80:83], v[150:153], v[204:207], v[80:83]
	v_mfma_f32_16x16x32_bf16 v[124:127], v[146:149], v[184:187], v[124:127]
	v_mfma_f32_16x16x32_bf16 v[120:123], v[154:157], v[184:187], v[120:123]
	v_mfma_f32_16x16x32_bf16 v[116:119], v[146:149], v[192:195], v[116:119]
	v_mfma_f32_16x16x32_bf16 v[112:115], v[154:157], v[192:195], v[112:115]
	v_mfma_f32_16x16x32_bf16 v[100:103], v[146:149], v[200:203], v[100:103]
	v_mfma_f32_16x16x32_bf16 v[96:99], v[154:157], v[200:203], v[96:99]
	v_mfma_f32_16x16x32_bf16 v[84:87], v[146:149], v[208:211], v[84:87]
	v_mfma_f32_16x16x32_bf16 v[80:83], v[154:157], v[208:211], v[80:83]
	s_setprio 0
	s_setprio 1
	v_mfma_f32_16x16x32_bf16 v[108:111], v[164:167], v[180:183], v[108:111]
	v_mfma_f32_16x16x32_bf16 v[104:107], v[172:175], v[180:183], v[104:107]
	v_mfma_f32_16x16x32_bf16 v[92:95], v[164:167], v[188:191], v[92:95]
	v_mfma_f32_16x16x32_bf16 v[88:91], v[172:175], v[188:191], v[88:91]
	v_mfma_f32_16x16x32_bf16 v[76:79], v[164:167], v[196:199], v[76:79]
	v_mfma_f32_16x16x32_bf16 v[72:75], v[172:175], v[196:199], v[72:75]
	v_mfma_f32_16x16x32_bf16 v[68:71], v[164:167], v[204:207], v[68:71]
	v_mfma_f32_16x16x32_bf16 v[64:67], v[172:175], v[204:207], v[64:67]
	v_mfma_f32_16x16x32_bf16 v[108:111], v[168:171], v[184:187], v[108:111]
	v_mfma_f32_16x16x32_bf16 v[104:107], v[176:179], v[184:187], v[104:107]
	v_mfma_f32_16x16x32_bf16 v[92:95], v[168:171], v[192:195], v[92:95]
	v_mfma_f32_16x16x32_bf16 v[88:91], v[176:179], v[192:195], v[88:91]
	v_mfma_f32_16x16x32_bf16 v[76:79], v[168:171], v[200:203], v[76:79]
	v_mfma_f32_16x16x32_bf16 v[72:75], v[176:179], v[200:203], v[72:75]
	v_mfma_f32_16x16x32_bf16 v[68:71], v[168:171], v[208:211], v[68:71]
	v_mfma_f32_16x16x32_bf16 v[64:67], v[176:179], v[208:211], v[64:67]
	s_setprio 0
	s_barrier
	s_add_i32 s78, s68, s58
	v_lshl_add_u64 v[214:215], s[48:49], 0, v[128:129]
	s_mov_b32 m0, s78
	ds_read_b128 v[180:183], v163 offset:16384
	ds_read_b128 v[184:187], v232 offset:16384
	ds_read_b128 v[188:191], v163 offset:18432
	ds_read_b128 v[192:195], v232 offset:18432
	ds_read_b128 v[196:199], v163 offset:20480
	ds_read_b128 v[200:203], v232 offset:20480
	ds_read_b128 v[204:207], v163 offset:22528
	ds_read_b128 v[208:211], v232 offset:22528
	global_load_lds_dwordx4 v[214:215], off
	s_add_i32 m0, s78, 0x2000
	s_add_u32 s78, s48, 0x100000
	v_lshl_add_u64 v[216:217], s[48:49], 0, v[130:131]
	s_addc_u32 s79, s49, 0
	s_add_i32 s80, s69, s58
	global_load_lds_dwordx4 v[216:217], off
	v_lshl_add_u64 v[218:219], s[78:79], 0, v[128:129]
	s_mov_b32 m0, s80
	v_lshl_add_u64 v[220:221], s[50:51], 0, v[130:131]
	global_load_lds_dwordx4 v[218:219], off
	v_lshl_add_u64 v[218:219], s[78:79], 0, v[130:131]
	s_add_i32 m0, s80, 0x2000
	s_nop 0
	global_load_lds_dwordx4 v[218:219], off
	v_lshl_add_u64 v[218:219], s[50:51], 0, v[128:129]
	s_mov_b32 m0, s19
	s_nop 0
	global_load_lds_dwordx4 v[218:219], off
	s_mov_b32 m0, s59
	s_nop 0
	global_load_lds_dwordx4 v[220:221], off
	s_waitcnt vmcnt(8)
	s_waitcnt lgkmcnt(0)
	s_barrier
	s_setprio 1
	s_waitcnt lgkmcnt(0)
	v_mfma_f32_16x16x32_bf16 v[60:63], v[142:145], v[180:183], v[60:63]
	v_mfma_f32_16x16x32_bf16 v[56:59], v[150:153], v[180:183], v[56:59]
	v_mfma_f32_16x16x32_bf16 v[52:55], v[142:145], v[188:191], v[52:55]
	v_mfma_f32_16x16x32_bf16 v[48:51], v[150:153], v[188:191], v[48:51]
	v_mfma_f32_16x16x32_bf16 v[36:39], v[142:145], v[196:199], v[36:39]
	v_mfma_f32_16x16x32_bf16 v[32:35], v[150:153], v[196:199], v[32:35]
	v_mfma_f32_16x16x32_bf16 v[20:23], v[142:145], v[204:207], v[20:23]
	v_mfma_f32_16x16x32_bf16 v[16:19], v[150:153], v[204:207], v[16:19]
	v_mfma_f32_16x16x32_bf16 v[60:63], v[146:149], v[184:187], v[60:63]
	v_mfma_f32_16x16x32_bf16 v[56:59], v[154:157], v[184:187], v[56:59]
	v_mfma_f32_16x16x32_bf16 v[52:55], v[146:149], v[192:195], v[52:55]
	v_mfma_f32_16x16x32_bf16 v[48:51], v[154:157], v[192:195], v[48:51]
	v_mfma_f32_16x16x32_bf16 v[36:39], v[146:149], v[200:203], v[36:39]
	v_mfma_f32_16x16x32_bf16 v[32:35], v[154:157], v[200:203], v[32:35]
	v_mfma_f32_16x16x32_bf16 v[20:23], v[146:149], v[208:211], v[20:23]
	v_mfma_f32_16x16x32_bf16 v[16:19], v[154:157], v[208:211], v[16:19]
	s_setprio 0
	s_setprio 1
	v_mfma_f32_16x16x32_bf16 v[44:47], v[164:167], v[180:183], v[44:47]
	v_mfma_f32_16x16x32_bf16 v[40:43], v[172:175], v[180:183], v[40:43]
	v_mfma_f32_16x16x32_bf16 v[28:31], v[164:167], v[188:191], v[28:31]
	v_mfma_f32_16x16x32_bf16 v[24:27], v[172:175], v[188:191], v[24:27]
	v_mfma_f32_16x16x32_bf16 v[12:15], v[164:167], v[196:199], v[12:15]
	v_mfma_f32_16x16x32_bf16 v[8:11], v[172:175], v[196:199], v[8:11]
	v_mfma_f32_16x16x32_bf16 v[4:7], v[164:167], v[204:207], v[4:7]
	v_mfma_f32_16x16x32_bf16 v[0:3], v[172:175], v[204:207], v[0:3]
	v_mfma_f32_16x16x32_bf16 v[44:47], v[168:171], v[184:187], v[44:47]
	v_mfma_f32_16x16x32_bf16 v[40:43], v[176:179], v[184:187], v[40:43]
	v_mfma_f32_16x16x32_bf16 v[28:31], v[168:171], v[192:195], v[28:31]
	v_mfma_f32_16x16x32_bf16 v[24:27], v[176:179], v[192:195], v[24:27]
	v_mfma_f32_16x16x32_bf16 v[12:15], v[168:171], v[200:203], v[12:15]
	v_mfma_f32_16x16x32_bf16 v[8:11], v[176:179], v[200:203], v[8:11]
	v_mfma_f32_16x16x32_bf16 v[4:7], v[168:171], v[208:211], v[4:7]
	v_mfma_f32_16x16x32_bf16 v[0:3], v[176:179], v[208:211], v[0:3]
	s_setprio 0
	s_barrier
	s_add_i32 s78, 0, 0x18000
	s_add_i32 s79, 0, 0x1c000
	v_add_u32_e32 v154, s78, v160
	v_add_u32_e32 v230, s78, v233
	v_add_u32_e32 v176, s79, v160
	v_add_u32_e32 v231, s79, v233
	ds_read_b128 v[142:145], v154
	ds_read_b128 v[146:149], v230
	ds_read_b128 v[150:153], v154 offset:2048
	ds_read_b128 v[154:157], v230 offset:2048
	ds_read_b128 v[164:167], v176
	ds_read_b128 v[168:171], v231
	ds_read_b128 v[172:175], v176 offset:2048
	ds_read_b128 v[176:179], v231 offset:2048
	s_add_u32 s50, s50, 0x100000
	s_addc_u32 s51, s51, 0
	s_mov_b32 m0, s60
	v_lshl_add_u64 v[222:223], s[50:51], 0, v[128:129]
	ds_read_b128 v[180:183], v163 offset:32768
	ds_read_b128 v[184:187], v232 offset:32768
	ds_read_b128 v[188:191], v163 offset:34816
	ds_read_b128 v[192:195], v232 offset:34816
	ds_read_b128 v[196:199], v163 offset:36864
	ds_read_b128 v[200:203], v232 offset:36864
	ds_read_b128 v[204:207], v163 offset:38912
	ds_read_b128 v[208:211], v232 offset:38912
	global_load_lds_dwordx4 v[222:223], off
	v_lshl_add_u64 v[222:223], s[50:51], 0, v[130:131]
	s_mov_b32 m0, s61
	s_nop 0
	global_load_lds_dwordx4 v[222:223], off
	s_waitcnt vmcnt(8)
	s_waitcnt lgkmcnt(0)
	s_barrier
	s_setprio 1
	s_waitcnt lgkmcnt(0)
	v_mfma_f32_16x16x32_bf16 v[124:127], v[142:145], v[180:183], v[124:127]
	v_mfma_f32_16x16x32_bf16 v[120:123], v[150:153], v[180:183], v[120:123]
	v_mfma_f32_16x16x32_bf16 v[116:119], v[142:145], v[188:191], v[116:119]
	v_mfma_f32_16x16x32_bf16 v[112:115], v[150:153], v[188:191], v[112:115]
	v_mfma_f32_16x16x32_bf16 v[100:103], v[142:145], v[196:199], v[100:103]
	v_mfma_f32_16x16x32_bf16 v[96:99], v[150:153], v[196:199], v[96:99]
	v_mfma_f32_16x16x32_bf16 v[84:87], v[142:145], v[204:207], v[84:87]
	v_mfma_f32_16x16x32_bf16 v[80:83], v[150:153], v[204:207], v[80:83]
	v_mfma_f32_16x16x32_bf16 v[124:127], v[146:149], v[184:187], v[124:127]
	v_mfma_f32_16x16x32_bf16 v[120:123], v[154:157], v[184:187], v[120:123]
	v_mfma_f32_16x16x32_bf16 v[116:119], v[146:149], v[192:195], v[116:119]
	v_mfma_f32_16x16x32_bf16 v[112:115], v[154:157], v[192:195], v[112:115]
	v_mfma_f32_16x16x32_bf16 v[100:103], v[146:149], v[200:203], v[100:103]
	v_mfma_f32_16x16x32_bf16 v[96:99], v[154:157], v[200:203], v[96:99]
	v_mfma_f32_16x16x32_bf16 v[84:87], v[146:149], v[208:211], v[84:87]
	v_mfma_f32_16x16x32_bf16 v[80:83], v[154:157], v[208:211], v[80:83]
	s_setprio 0
	s_setprio 1
	v_mfma_f32_16x16x32_bf16 v[108:111], v[164:167], v[180:183], v[108:111]
	v_mfma_f32_16x16x32_bf16 v[104:107], v[172:175], v[180:183], v[104:107]
	v_mfma_f32_16x16x32_bf16 v[92:95], v[164:167], v[188:191], v[92:95]
	v_mfma_f32_16x16x32_bf16 v[88:91], v[172:175], v[188:191], v[88:91]
	v_mfma_f32_16x16x32_bf16 v[76:79], v[164:167], v[196:199], v[76:79]
	v_mfma_f32_16x16x32_bf16 v[72:75], v[172:175], v[196:199], v[72:75]
	v_mfma_f32_16x16x32_bf16 v[68:71], v[164:167], v[204:207], v[68:71]
	v_mfma_f32_16x16x32_bf16 v[64:67], v[172:175], v[204:207], v[64:67]
	v_mfma_f32_16x16x32_bf16 v[108:111], v[168:171], v[184:187], v[108:111]
	v_mfma_f32_16x16x32_bf16 v[104:107], v[176:179], v[184:187], v[104:107]
	v_mfma_f32_16x16x32_bf16 v[92:95], v[168:171], v[192:195], v[92:95]
	v_mfma_f32_16x16x32_bf16 v[88:91], v[176:179], v[192:195], v[88:91]
	v_mfma_f32_16x16x32_bf16 v[76:79], v[168:171], v[200:203], v[76:79]
	v_mfma_f32_16x16x32_bf16 v[72:75], v[176:179], v[200:203], v[72:75]
	v_mfma_f32_16x16x32_bf16 v[68:71], v[168:171], v[208:211], v[68:71]
	v_mfma_f32_16x16x32_bf16 v[64:67], v[176:179], v[208:211], v[64:67]
	s_setprio 0
	s_barrier
; template <class Epi, class Sched, bool FP8 = false>
; __device__ __forceinline__ void gemm_phase(LAS unsigned char* lds, const Gemm g, const Sched& S, const Epi& E, const int tid) {
;     ...
;         for (int t = 0; t < nt; t += 2) PG8_KBODY(t);
	s_add_i32 s50, s78, s58
	v_lshl_add_u64 v[214:215], v[214:215], 0, s[14:15]
	s_mov_b32 m0, s50
	ds_read_b128 v[180:183], v163 offset:49152
	ds_read_b128 v[184:187], v232 offset:49152
	ds_read_b128 v[188:191], v163 offset:51200
	ds_read_b128 v[192:195], v232 offset:51200
	ds_read_b128 v[196:199], v163 offset:53248
	ds_read_b128 v[200:203], v232 offset:53248
	ds_read_b128 v[204:207], v163 offset:55296
	ds_read_b128 v[208:211], v232 offset:55296
	global_load_lds_dwordx4 v[214:215], off
	s_add_i32 m0, s50, 0x2000
	s_add_u32 s48, s48, 0x100080
	v_lshl_add_u64 v[214:215], v[216:217], 0, s[14:15]
	s_addc_u32 s49, s49, 0
	s_add_i32 s50, s79, s58
	global_load_lds_dwordx4 v[214:215], off
	v_lshl_add_u64 v[214:215], s[48:49], 0, v[128:129]
	s_mov_b32 m0, s50
	s_nop 0
	global_load_lds_dwordx4 v[214:215], off
	v_lshl_add_u64 v[214:215], s[48:49], 0, v[130:131]
	s_add_i32 m0, s50, 0x2000
	s_nop 0
	global_load_lds_dwordx4 v[214:215], off
	v_lshl_add_u64 v[214:215], v[218:219], 0, s[14:15]
	s_mov_b32 m0, s66
	s_nop 0
	global_load_lds_dwordx4 v[214:215], off
	v_lshl_add_u64 v[214:215], v[220:221], 0, s[14:15]
	s_mov_b32 m0, s67
	s_nop 0
	global_load_lds_dwordx4 v[214:215], off
	s_waitcnt vmcnt(8)
	s_waitcnt lgkmcnt(0)
	s_barrier
	s_setprio 1
	s_waitcnt lgkmcnt(0)
	v_mfma_f32_16x16x32_bf16 v[60:63], v[142:145], v[180:183], v[60:63]
	v_mfma_f32_16x16x32_bf16 v[56:59], v[150:153], v[180:183], v[56:59]
	v_mfma_f32_16x16x32_bf16 v[52:55], v[142:145], v[188:191], v[52:55]
	v_mfma_f32_16x16x32_bf16 v[48:51], v[150:153], v[188:191], v[48:51]
	v_mfma_f32_16x16x32_bf16 v[36:39], v[142:145], v[196:199], v[36:39]
	v_mfma_f32_16x16x32_bf16 v[32:35], v[150:153], v[196:199], v[32:35]
	v_mfma_f32_16x16x32_bf16 v[20:23], v[142:145], v[204:207], v[20:23]
	v_mfma_f32_16x16x32_bf16 v[16:19], v[150:153], v[204:207], v[16:19]
	v_mfma_f32_16x16x32_bf16 v[60:63], v[146:149], v[184:187], v[60:63]
	v_mfma_f32_16x16x32_bf16 v[56:59], v[154:157], v[184:187], v[56:59]
	v_mfma_f32_16x16x32_bf16 v[52:55], v[146:149], v[192:195], v[52:55]
	v_mfma_f32_16x16x32_bf16 v[48:51], v[154:157], v[192:195], v[48:51]
	v_mfma_f32_16x16x32_bf16 v[36:39], v[146:149], v[200:203], v[36:39]
	v_mfma_f32_16x16x32_bf16 v[32:35], v[154:157], v[200:203], v[32:35]
	v_mfma_f32_16x16x32_bf16 v[20:23], v[146:149], v[208:211], v[20:23]
	v_mfma_f32_16x16x32_bf16 v[16:19], v[154:157], v[208:211], v[16:19]
	s_setprio 0
	s_setprio 1
	v_mfma_f32_16x16x32_bf16 v[44:47], v[164:167], v[180:183], v[44:47]
	v_mfma_f32_16x16x32_bf16 v[40:43], v[172:175], v[180:183], v[40:43]
	v_mfma_f32_16x16x32_bf16 v[28:31], v[164:167], v[188:191], v[28:31]
	v_mfma_f32_16x16x32_bf16 v[24:27], v[172:175], v[188:191], v[24:27]
	v_mfma_f32_16x16x32_bf16 v[12:15], v[164:167], v[196:199], v[12:15]
	v_mfma_f32_16x16x32_bf16 v[8:11], v[172:175], v[196:199], v[8:11]
	v_mfma_f32_16x16x32_bf16 v[4:7], v[164:167], v[204:207], v[4:7]
	v_mfma_f32_16x16x32_bf16 v[0:3], v[172:175], v[204:207], v[0:3]
	v_mfma_f32_16x16x32_bf16 v[44:47], v[168:171], v[184:187], v[44:47]
	v_mfma_f32_16x16x32_bf16 v[40:43], v[176:179], v[184:187], v[40:43]
	v_mfma_f32_16x16x32_bf16 v[28:31], v[168:171], v[192:195], v[28:31]
	v_mfma_f32_16x16x32_bf16 v[24:27], v[176:179], v[192:195], v[24:27]
	v_mfma_f32_16x16x32_bf16 v[12:15], v[168:171], v[200:203], v[12:15]
	v_mfma_f32_16x16x32_bf16 v[8:11], v[176:179], v[200:203], v[8:11]
	v_mfma_f32_16x16x32_bf16 v[4:7], v[168:171], v[208:211], v[4:7]
	v_mfma_f32_16x16x32_bf16 v[0:3], v[176:179], v[208:211], v[0:3]
	s_setprio 0
	s_add_i32 s77, s77, 2
	s_add_u32 s46, s46, 0x100
	s_addc_u32 s47, s47, 0
	s_add_u32 s75, s75, 0x100
	s_addc_u32 s76, s76, 0
	s_cmp_gt_u32 s77, 61
	s_barrier
	s_cbranch_scc0 .LBB0_101
	s_and_b64 vcc, exec, s[16:17]
	s_cbranch_vccz .LBB0_104
	s_barrier

.LBB0_157:
	ds_read_b128 v[24:27], v184
	ds_read_b128 v[28:31], v234
	ds_read_b128 v[16:19], v184 offset:2048
	ds_read_b128 v[20:23], v234 offset:2048
	ds_read_b128 v[8:11], v185
	ds_read_b128 v[12:15], v235
	ds_read_b128 v[0:3], v185 offset:2048
	ds_read_b128 v[4:7], v235 offset:2048
	s_add_u32 s42, s28, 0xfff80080
	s_addc_u32 s43, s29, -1
	s_cmp_eq_u32 s81, 28
	s_cselect_b32 s45, s21, s43
	s_cselect_b32 s44, s77, s42
	s_cselect_b32 s43, s19, s80
	s_cselect_b32 s42, s78, s79
	v_lshl_add_u64 v[214:215], s[28:29], 0, v[166:167]
	s_add_i32 m0, s51, 0xc000
	ds_read_b128 v[174:177], v186
	ds_read_b128 v[178:181], v232
	ds_read_b128 v[188:191], v186 offset:2048
	ds_read_b128 v[192:195], v232 offset:2048
	ds_read_b128 v[196:199], v186 offset:4096
	ds_read_b128 v[200:203], v232 offset:4096
	ds_read_b128 v[204:207], v186 offset:6144
	ds_read_b128 v[208:211], v232 offset:6144
	global_load_lds_dwordx4 v[214:215], off
	v_lshl_add_u64 v[214:215], s[28:29], 0, v[168:169]
	s_add_i32 m0, s51, 0xe000
	s_nop 0
	global_load_lds_dwordx4 v[214:215], off
	s_waitcnt vmcnt(8)
	s_waitcnt lgkmcnt(0)
	s_barrier
	s_setprio 1
	s_waitcnt lgkmcnt(0)
	v_mfma_scale_f32_16x16x128_f8f6f4 v[156:159], v[24:31], v[174:181], v[156:159], v187, v187 op_sel_hi:[0,0,0]
	v_mfma_scale_f32_16x16x128_f8f6f4 v[152:155], v[16:23], v[174:181], v[152:155], v187, v187 op_sel_hi:[0,0,0]
	v_mfma_scale_f32_16x16x128_f8f6f4 v[140:143], v[24:31], v[188:195], v[140:143], v187, v187 op_sel_hi:[0,0,0]
	v_mfma_scale_f32_16x16x128_f8f6f4 v[136:139], v[16:23], v[188:195], v[136:139], v187, v187 op_sel_hi:[0,0,0]
	v_mfma_scale_f32_16x16x128_f8f6f4 v[124:127], v[24:31], v[196:203], v[124:127], v187, v187 op_sel_hi:[0,0,0]
	v_mfma_scale_f32_16x16x128_f8f6f4 v[120:123], v[16:23], v[196:203], v[120:123], v187, v187 op_sel_hi:[0,0,0]
	v_mfma_scale_f32_16x16x128_f8f6f4 v[108:111], v[24:31], v[204:211], v[108:111], v187, v187 op_sel_hi:[0,0,0]
	v_mfma_scale_f32_16x16x128_f8f6f4 v[104:107], v[16:23], v[204:211], v[104:107], v187, v187 op_sel_hi:[0,0,0]
	s_setprio 0
	s_setprio 1
	v_mfma_scale_f32_16x16x128_f8f6f4 v[148:151], v[8:15], v[174:181], v[148:151], v187, v187 op_sel_hi:[0,0,0]
	v_mfma_scale_f32_16x16x128_f8f6f4 v[144:147], v[0:7], v[174:181], v[144:147], v187, v187 op_sel_hi:[0,0,0]
	v_mfma_scale_f32_16x16x128_f8f6f4 v[132:135], v[8:15], v[188:195], v[132:135], v187, v187 op_sel_hi:[0,0,0]
	v_mfma_scale_f32_16x16x128_f8f6f4 v[128:131], v[0:7], v[188:195], v[128:131], v187, v187 op_sel_hi:[0,0,0]
	v_mfma_scale_f32_16x16x128_f8f6f4 v[116:119], v[8:15], v[196:203], v[116:119], v187, v187 op_sel_hi:[0,0,0]
	v_mfma_scale_f32_16x16x128_f8f6f4 v[112:115], v[0:7], v[196:203], v[112:115], v187, v187 op_sel_hi:[0,0,0]
	v_mfma_scale_f32_16x16x128_f8f6f4 v[100:103], v[8:15], v[204:211], v[100:103], v187, v187 op_sel_hi:[0,0,0]
	v_mfma_scale_f32_16x16x128_f8f6f4 v[96:99], v[0:7], v[204:211], v[96:99], v187, v187 op_sel_hi:[0,0,0]
	s_setprio 0
	s_barrier
	s_add_i32 s82, s74, s46
	v_lshl_add_u64 v[174:175], s[42:43], 0, v[162:163]
	s_mov_b32 m0, s82
	ds_read_b128 v[188:191], v186 offset:16384
	ds_read_b128 v[192:195], v232 offset:16384
	ds_read_b128 v[196:199], v186 offset:18432
	ds_read_b128 v[200:203], v232 offset:18432
	ds_read_b128 v[204:207], v186 offset:20480
	ds_read_b128 v[208:211], v232 offset:20480
	ds_read_b128 v[214:217], v186 offset:22528
	ds_read_b128 v[218:221], v232 offset:22528
	global_load_lds_dwordx4 v[174:175], off
	s_add_i32 m0, s82, 0x2000
	s_add_u32 s82, s42, 0x80000
	v_lshl_add_u64 v[176:177], s[42:43], 0, v[160:161]
	s_addc_u32 s83, s43, 0
	s_add_i32 s84, s75, s46
	global_load_lds_dwordx4 v[176:177], off
	v_lshl_add_u64 v[178:179], s[82:83], 0, v[162:163]
	s_mov_b32 m0, s84
	v_lshl_add_u64 v[180:181], s[44:45], 0, v[160:161]
	global_load_lds_dwordx4 v[178:179], off
	v_lshl_add_u64 v[178:179], s[82:83], 0, v[160:161]
	s_add_i32 m0, s84, 0x2000
	s_nop 0
	global_load_lds_dwordx4 v[178:179], off
	v_lshl_add_u64 v[178:179], s[44:45], 0, v[162:163]
	s_mov_b32 m0, s51
	s_nop 0
	global_load_lds_dwordx4 v[178:179], off
	s_mov_b32 m0, s54
	s_nop 0
	global_load_lds_dwordx4 v[180:181], off
	s_waitcnt vmcnt(8)
	s_waitcnt lgkmcnt(0)
	s_barrier
	s_setprio 1
	s_waitcnt lgkmcnt(0)
	v_mfma_scale_f32_16x16x128_f8f6f4 v[92:95], v[24:31], v[188:195], v[92:95], v187, v187 op_sel_hi:[0,0,0]
	v_mfma_scale_f32_16x16x128_f8f6f4 v[88:91], v[16:23], v[188:195], v[88:91], v187, v187 op_sel_hi:[0,0,0]
	v_mfma_scale_f32_16x16x128_f8f6f4 v[76:79], v[24:31], v[196:203], v[76:79], v187, v187 op_sel_hi:[0,0,0]
	v_mfma_scale_f32_16x16x128_f8f6f4 v[72:75], v[16:23], v[196:203], v[72:75], v187, v187 op_sel_hi:[0,0,0]
	v_mfma_scale_f32_16x16x128_f8f6f4 v[60:63], v[24:31], v[204:211], v[60:63], v187, v187 op_sel_hi:[0,0,0]
	v_mfma_scale_f32_16x16x128_f8f6f4 v[56:59], v[16:23], v[204:211], v[56:59], v187, v187 op_sel_hi:[0,0,0]
	v_mfma_scale_f32_16x16x128_f8f6f4 v[44:47], v[24:31], v[214:221], v[44:47], v187, v187 op_sel_hi:[0,0,0]
	v_mfma_scale_f32_16x16x128_f8f6f4 v[40:43], v[16:23], v[214:221], v[40:43], v187, v187 op_sel_hi:[0,0,0]
	s_setprio 0
	s_setprio 1
	v_mfma_scale_f32_16x16x128_f8f6f4 v[84:87], v[8:15], v[188:195], v[84:87], v187, v187 op_sel_hi:[0,0,0]
	v_mfma_scale_f32_16x16x128_f8f6f4 v[80:83], v[0:7], v[188:195], v[80:83], v187, v187 op_sel_hi:[0,0,0]
	v_mfma_scale_f32_16x16x128_f8f6f4 v[68:71], v[8:15], v[196:203], v[68:71], v187, v187 op_sel_hi:[0,0,0]
	v_mfma_scale_f32_16x16x128_f8f6f4 v[64:67], v[0:7], v[196:203], v[64:67], v187, v187 op_sel_hi:[0,0,0]
	v_mfma_scale_f32_16x16x128_f8f6f4 v[52:55], v[8:15], v[204:211], v[52:55], v187, v187 op_sel_hi:[0,0,0]
	v_mfma_scale_f32_16x16x128_f8f6f4 v[48:51], v[0:7], v[204:211], v[48:51], v187, v187 op_sel_hi:[0,0,0]
	v_mfma_scale_f32_16x16x128_f8f6f4 v[36:39], v[8:15], v[214:221], v[36:39], v187, v187 op_sel_hi:[0,0,0]
	v_mfma_scale_f32_16x16x128_f8f6f4 v[32:35], v[0:7], v[214:221], v[32:35], v187, v187 op_sel_hi:[0,0,0]
	s_setprio 0
	s_barrier
; template <class Epi, class Sched, bool FP8 = false>
; __device__ __forceinline__ void gemm_phase(LAS unsigned char* lds, const Gemm g, const Sched& S, const Epi& E, const int tid) {
;     ...
;         for (int t = 0; t < nt; t += 2) PG8_KBODY(t);
	s_add_i32 s82, 0, 0x18000
	s_add_i32 s83, 0, 0x1c000
	v_add_u32_e32 v12, s82, v182
	v_add_u32_e32 v230, s82, v233
	v_add_u32_e32 v28, s83, v182
	v_add_u32_e32 v231, s83, v233
	ds_read_b128 v[0:3], v12
	ds_read_b128 v[4:7], v230
	ds_read_b128 v[8:11], v12 offset:2048
	ds_read_b128 v[12:15], v230 offset:2048
	ds_read_b128 v[16:19], v28
	ds_read_b128 v[20:23], v231
	ds_read_b128 v[24:27], v28 offset:2048
	ds_read_b128 v[28:31], v231 offset:2048
	s_add_u32 s44, s44, 0x80000
	s_addc_u32 s45, s45, 0
	s_mov_b32 m0, s55
	v_lshl_add_u64 v[222:223], s[44:45], 0, v[162:163]
	ds_read_b128 v[188:191], v186 offset:32768
	ds_read_b128 v[192:195], v232 offset:32768
	ds_read_b128 v[196:199], v186 offset:34816
	ds_read_b128 v[200:203], v232 offset:34816
	ds_read_b128 v[204:207], v186 offset:36864
	ds_read_b128 v[208:211], v232 offset:36864
	ds_read_b128 v[214:217], v186 offset:38912
	ds_read_b128 v[218:221], v232 offset:38912
	global_load_lds_dwordx4 v[222:223], off
	v_lshl_add_u64 v[222:223], s[44:45], 0, v[160:161]
	s_mov_b32 m0, s56
	s_nop 0
	global_load_lds_dwordx4 v[222:223], off
	s_waitcnt vmcnt(8)
	s_waitcnt lgkmcnt(0)
	s_barrier
	s_setprio 1
	s_waitcnt lgkmcnt(0)
	v_mfma_scale_f32_16x16x128_f8f6f4 v[156:159], v[0:7], v[188:195], v[156:159], v187, v187 op_sel_hi:[0,0,0]
	v_mfma_scale_f32_16x16x128_f8f6f4 v[152:155], v[8:15], v[188:195], v[152:155], v187, v187 op_sel_hi:[0,0,0]
	v_mfma_scale_f32_16x16x128_f8f6f4 v[140:143], v[0:7], v[196:203], v[140:143], v187, v187 op_sel_hi:[0,0,0]
	v_mfma_scale_f32_16x16x128_f8f6f4 v[136:139], v[8:15], v[196:203], v[136:139], v187, v187 op_sel_hi:[0,0,0]
	v_mfma_scale_f32_16x16x128_f8f6f4 v[124:127], v[0:7], v[204:211], v[124:127], v187, v187 op_sel_hi:[0,0,0]
	v_mfma_scale_f32_16x16x128_f8f6f4 v[120:123], v[8:15], v[204:211], v[120:123], v187, v187 op_sel_hi:[0,0,0]
	v_mfma_scale_f32_16x16x128_f8f6f4 v[108:111], v[0:7], v[214:221], v[108:111], v187, v187 op_sel_hi:[0,0,0]
	v_mfma_scale_f32_16x16x128_f8f6f4 v[104:107], v[8:15], v[214:221], v[104:107], v187, v187 op_sel_hi:[0,0,0]
	s_setprio 0
	s_setprio 1
	v_mfma_scale_f32_16x16x128_f8f6f4 v[148:151], v[16:23], v[188:195], v[148:151], v187, v187 op_sel_hi:[0,0,0]
	v_mfma_scale_f32_16x16x128_f8f6f4 v[144:147], v[24:31], v[188:195], v[144:147], v187, v187 op_sel_hi:[0,0,0]
	v_mfma_scale_f32_16x16x128_f8f6f4 v[132:135], v[16:23], v[196:203], v[132:135], v187, v187 op_sel_hi:[0,0,0]
	v_mfma_scale_f32_16x16x128_f8f6f4 v[128:131], v[24:31], v[196:203], v[128:131], v187, v187 op_sel_hi:[0,0,0]
	v_mfma_scale_f32_16x16x128_f8f6f4 v[116:119], v[16:23], v[204:211], v[116:119], v187, v187 op_sel_hi:[0,0,0]
	v_mfma_scale_f32_16x16x128_f8f6f4 v[112:115], v[24:31], v[204:211], v[112:115], v187, v187 op_sel_hi:[0,0,0]
	v_mfma_scale_f32_16x16x128_f8f6f4 v[100:103], v[16:23], v[214:221], v[100:103], v187, v187 op_sel_hi:[0,0,0]
	v_mfma_scale_f32_16x16x128_f8f6f4 v[96:99], v[24:31], v[214:221], v[96:99], v187, v187 op_sel_hi:[0,0,0]
	s_setprio 0
	s_barrier
	s_add_i32 s44, s82, s46
	v_lshl_add_u64 v[174:175], v[174:175], 0, s[10:11]
	s_mov_b32 m0, s44
	ds_read_b128 v[188:191], v186 offset:49152
	ds_read_b128 v[192:195], v232 offset:49152
	ds_read_b128 v[196:199], v186 offset:51200
	ds_read_b128 v[200:203], v232 offset:51200
	ds_read_b128 v[204:207], v186 offset:53248
	ds_read_b128 v[208:211], v232 offset:53248
	ds_read_b128 v[214:217], v186 offset:55296
	ds_read_b128 v[218:221], v232 offset:55296
	global_load_lds_dwordx4 v[174:175], off
	s_add_i32 m0, s44, 0x2000
	s_add_u32 s42, s42, 0x80080
	v_lshl_add_u64 v[174:175], v[176:177], 0, s[10:11]
	s_addc_u32 s43, s43, 0
	s_add_i32 s44, s83, s46
	global_load_lds_dwordx4 v[174:175], off
	v_lshl_add_u64 v[174:175], s[42:43], 0, v[162:163]
	s_mov_b32 m0, s44
	s_nop 0
	global_load_lds_dwordx4 v[174:175], off
	v_lshl_add_u64 v[174:175], s[42:43], 0, v[160:161]
	s_add_i32 m0, s44, 0x2000
	s_nop 0
	global_load_lds_dwordx4 v[174:175], off
	v_lshl_add_u64 v[174:175], v[178:179], 0, s[10:11]
	s_mov_b32 m0, s67
	s_nop 0
	global_load_lds_dwordx4 v[174:175], off
	v_lshl_add_u64 v[174:175], v[180:181], 0, s[10:11]
	s_mov_b32 m0, s68
	s_nop 0
	global_load_lds_dwordx4 v[174:175], off
	s_waitcnt vmcnt(8)
	s_waitcnt lgkmcnt(0)
	s_barrier
	s_setprio 1
	s_waitcnt lgkmcnt(0)
	v_mfma_scale_f32_16x16x128_f8f6f4 v[92:95], v[0:7], v[188:195], v[92:95], v187, v187 op_sel_hi:[0,0,0]
	v_mfma_scale_f32_16x16x128_f8f6f4 v[88:91], v[8:15], v[188:195], v[88:91], v187, v187 op_sel_hi:[0,0,0]
	v_mfma_scale_f32_16x16x128_f8f6f4 v[76:79], v[0:7], v[196:203], v[76:79], v187, v187 op_sel_hi:[0,0,0]
	v_mfma_scale_f32_16x16x128_f8f6f4 v[72:75], v[8:15], v[196:203], v[72:75], v187, v187 op_sel_hi:[0,0,0]
	v_mfma_scale_f32_16x16x128_f8f6f4 v[60:63], v[0:7], v[204:211], v[60:63], v187, v187 op_sel_hi:[0,0,0]
	v_mfma_scale_f32_16x16x128_f8f6f4 v[56:59], v[8:15], v[204:211], v[56:59], v187, v187 op_sel_hi:[0,0,0]
	v_mfma_scale_f32_16x16x128_f8f6f4 v[44:47], v[0:7], v[214:221], v[44:47], v187, v187 op_sel_hi:[0,0,0]
	v_mfma_scale_f32_16x16x128_f8f6f4 v[40:43], v[8:15], v[214:221], v[40:43], v187, v187 op_sel_hi:[0,0,0]
	s_setprio 0
	s_setprio 1
	v_mfma_scale_f32_16x16x128_f8f6f4 v[84:87], v[16:23], v[188:195], v[84:87], v187, v187 op_sel_hi:[0,0,0]
	v_mfma_scale_f32_16x16x128_f8f6f4 v[80:83], v[24:31], v[188:195], v[80:83], v187, v187 op_sel_hi:[0,0,0]
	v_mfma_scale_f32_16x16x128_f8f6f4 v[68:71], v[16:23], v[196:203], v[68:71], v187, v187 op_sel_hi:[0,0,0]
	v_mfma_scale_f32_16x16x128_f8f6f4 v[64:67], v[24:31], v[196:203], v[64:67], v187, v187 op_sel_hi:[0,0,0]
	v_mfma_scale_f32_16x16x128_f8f6f4 v[52:55], v[16:23], v[204:211], v[52:55], v187, v187 op_sel_hi:[0,0,0]
	v_mfma_scale_f32_16x16x128_f8f6f4 v[48:51], v[24:31], v[204:211], v[48:51], v187, v187 op_sel_hi:[0,0,0]
	v_mfma_scale_f32_16x16x128_f8f6f4 v[36:39], v[16:23], v[214:221], v[36:39], v187, v187 op_sel_hi:[0,0,0]
	v_mfma_scale_f32_16x16x128_f8f6f4 v[32:35], v[24:31], v[214:221], v[32:35], v187, v187 op_sel_hi:[0,0,0]
	s_setprio 0
	s_add_i32 s81, s81, 2
	s_add_u32 s28, s28, 0x100
	s_addc_u32 s29, s29, 0
	s_add_u32 s79, s79, 0x100
	s_addc_u32 s80, s80, 0
	s_cmp_gt_u32 s81, 29
	s_barrier
	s_cbranch_scc0 .LBB0_157
	s_and_b64 vcc, exec, s[12:13]
	s_cbranch_vccz .LBB0_160
	s_barrier

.LBB0_471:
	v_add_u32_e32 v154, s69, v214
	v_add_u32_e32 v230, s69, v233
	v_add_u32_e32 v170, s70, v214
	v_add_u32_e32 v231, s70, v233
	ds_read_b128 v[142:145], v154
	ds_read_b128 v[146:149], v230
	ds_read_b128 v[150:153], v154 offset:2048
	ds_read_b128 v[154:157], v230 offset:2048
	ds_read_b128 v[158:161], v170
	ds_read_b128 v[162:165], v231
	ds_read_b128 v[166:169], v170 offset:2048
	ds_read_b128 v[170:173], v231 offset:2048
	s_add_u32 s46, s4, 0xfff00080
	s_addc_u32 s47, s5, -1
	s_cmp_eq_u32 s85, 28
	s_cselect_b32 s49, s29, s47
	s_cselect_b32 s48, s81, s46
	s_cselect_b32 s47, s27, s84
	s_cselect_b32 s46, s82, s83
	v_lshl_add_u64 v[206:207], s[4:5], 0, v[134:135]
	s_add_i32 m0, s55, 0xc000
	ds_read_b128 v[174:177], v216
	ds_read_b128 v[178:181], v232
	ds_read_b128 v[182:185], v216 offset:2048
	ds_read_b128 v[186:189], v232 offset:2048
	ds_read_b128 v[190:193], v216 offset:4096
	ds_read_b128 v[194:197], v232 offset:4096
	ds_read_b128 v[198:201], v216 offset:6144
	ds_read_b128 v[202:205], v232 offset:6144
	global_load_lds_dwordx4 v[206:207], off
	v_lshl_add_u64 v[206:207], s[4:5], 0, v[136:137]
	s_add_i32 m0, s55, 0xe000
	s_nop 0
	global_load_lds_dwordx4 v[206:207], off
	s_waitcnt vmcnt(8)
	s_waitcnt lgkmcnt(0)
	s_barrier
	s_setprio 1
	s_waitcnt lgkmcnt(0)
	v_mfma_f32_16x16x32_bf16 v[124:127], v[142:145], v[174:177], v[124:127]
	v_mfma_f32_16x16x32_bf16 v[120:123], v[150:153], v[174:177], v[120:123]
	v_mfma_f32_16x16x32_bf16 v[116:119], v[142:145], v[182:185], v[116:119]
	v_mfma_f32_16x16x32_bf16 v[112:115], v[150:153], v[182:185], v[112:115]
	v_mfma_f32_16x16x32_bf16 v[108:111], v[142:145], v[190:193], v[108:111]
	v_mfma_f32_16x16x32_bf16 v[104:107], v[150:153], v[190:193], v[104:107]
	v_mfma_f32_16x16x32_bf16 v[100:103], v[142:145], v[198:201], v[100:103]
	v_mfma_f32_16x16x32_bf16 v[96:99], v[150:153], v[198:201], v[96:99]
	v_mfma_f32_16x16x32_bf16 v[124:127], v[146:149], v[178:181], v[124:127]
	v_mfma_f32_16x16x32_bf16 v[120:123], v[154:157], v[178:181], v[120:123]
	v_mfma_f32_16x16x32_bf16 v[116:119], v[146:149], v[186:189], v[116:119]
	v_mfma_f32_16x16x32_bf16 v[112:115], v[154:157], v[186:189], v[112:115]
	v_mfma_f32_16x16x32_bf16 v[108:111], v[146:149], v[194:197], v[108:111]
	v_mfma_f32_16x16x32_bf16 v[104:107], v[154:157], v[194:197], v[104:107]
	v_mfma_f32_16x16x32_bf16 v[100:103], v[146:149], v[202:205], v[100:103]
	v_mfma_f32_16x16x32_bf16 v[96:99], v[154:157], v[202:205], v[96:99]
	s_setprio 0
	s_setprio 1
	v_mfma_f32_16x16x32_bf16 v[92:95], v[158:161], v[174:177], v[92:95]
	v_mfma_f32_16x16x32_bf16 v[88:91], v[166:169], v[174:177], v[88:91]
	v_mfma_f32_16x16x32_bf16 v[84:87], v[158:161], v[182:185], v[84:87]
	v_mfma_f32_16x16x32_bf16 v[80:83], v[166:169], v[182:185], v[80:83]
	v_mfma_f32_16x16x32_bf16 v[76:79], v[158:161], v[190:193], v[76:79]
	v_mfma_f32_16x16x32_bf16 v[72:75], v[166:169], v[190:193], v[72:75]
	v_mfma_f32_16x16x32_bf16 v[68:71], v[158:161], v[198:201], v[68:71]
	v_mfma_f32_16x16x32_bf16 v[64:67], v[166:169], v[198:201], v[64:67]
	v_mfma_f32_16x16x32_bf16 v[92:95], v[162:165], v[178:181], v[92:95]
	v_mfma_f32_16x16x32_bf16 v[88:91], v[170:173], v[178:181], v[88:91]
	v_mfma_f32_16x16x32_bf16 v[84:87], v[162:165], v[186:189], v[84:87]
	v_mfma_f32_16x16x32_bf16 v[80:83], v[170:173], v[186:189], v[80:83]
	v_mfma_f32_16x16x32_bf16 v[76:79], v[162:165], v[194:197], v[76:79]
	v_mfma_f32_16x16x32_bf16 v[72:75], v[170:173], v[194:197], v[72:75]
	v_mfma_f32_16x16x32_bf16 v[68:71], v[162:165], v[202:205], v[68:71]
	v_mfma_f32_16x16x32_bf16 v[64:67], v[170:173], v[202:205], v[64:67]
	s_setprio 0
	s_barrier
	s_add_i32 s86, s69, s54
	v_lshl_add_u64 v[206:207], s[46:47], 0, v[130:131]
	s_mov_b32 m0, s86
	ds_read_b128 v[174:177], v216 offset:16384
	ds_read_b128 v[178:181], v232 offset:16384
	ds_read_b128 v[182:185], v216 offset:18432
	ds_read_b128 v[186:189], v232 offset:18432
	ds_read_b128 v[190:193], v216 offset:20480
	ds_read_b128 v[194:197], v232 offset:20480
	ds_read_b128 v[198:201], v216 offset:22528
	ds_read_b128 v[202:205], v232 offset:22528
	global_load_lds_dwordx4 v[206:207], off
	s_add_i32 m0, s86, 0x2000
	s_add_u32 s86, s46, 0x100000
	v_lshl_add_u64 v[208:209], s[46:47], 0, v[128:129]
	s_addc_u32 s87, s47, 0
	s_add_i32 s88, s70, s54
	global_load_lds_dwordx4 v[208:209], off
	v_lshl_add_u64 v[210:211], s[86:87], 0, v[130:131]
	s_mov_b32 m0, s88
	v_lshl_add_u64 v[218:219], s[48:49], 0, v[128:129]
	global_load_lds_dwordx4 v[210:211], off
	v_lshl_add_u64 v[210:211], s[86:87], 0, v[128:129]
	s_add_i32 m0, s88, 0x2000
	s_nop 0
	global_load_lds_dwordx4 v[210:211], off
	v_lshl_add_u64 v[210:211], s[48:49], 0, v[130:131]
	s_mov_b32 m0, s55
	s_nop 0
	global_load_lds_dwordx4 v[210:211], off
	s_mov_b32 m0, s56
	s_nop 0
	global_load_lds_dwordx4 v[218:219], off
	s_waitcnt vmcnt(8)
	s_waitcnt lgkmcnt(0)
	s_barrier
	s_setprio 1
	s_waitcnt lgkmcnt(0)
	v_mfma_f32_16x16x32_bf16 v[60:63], v[142:145], v[174:177], v[60:63]
	v_mfma_f32_16x16x32_bf16 v[56:59], v[150:153], v[174:177], v[56:59]
	v_mfma_f32_16x16x32_bf16 v[52:55], v[142:145], v[182:185], v[52:55]
	v_mfma_f32_16x16x32_bf16 v[48:51], v[150:153], v[182:185], v[48:51]
	v_mfma_f32_16x16x32_bf16 v[44:47], v[142:145], v[190:193], v[44:47]
	v_mfma_f32_16x16x32_bf16 v[40:43], v[150:153], v[190:193], v[40:43]
	v_mfma_f32_16x16x32_bf16 v[36:39], v[142:145], v[198:201], v[36:39]
	v_mfma_f32_16x16x32_bf16 v[32:35], v[150:153], v[198:201], v[32:35]
	v_mfma_f32_16x16x32_bf16 v[60:63], v[146:149], v[178:181], v[60:63]
	v_mfma_f32_16x16x32_bf16 v[56:59], v[154:157], v[178:181], v[56:59]
	v_mfma_f32_16x16x32_bf16 v[52:55], v[146:149], v[186:189], v[52:55]
	v_mfma_f32_16x16x32_bf16 v[48:51], v[154:157], v[186:189], v[48:51]
	v_mfma_f32_16x16x32_bf16 v[44:47], v[146:149], v[194:197], v[44:47]
	v_mfma_f32_16x16x32_bf16 v[40:43], v[154:157], v[194:197], v[40:43]
	v_mfma_f32_16x16x32_bf16 v[36:39], v[146:149], v[202:205], v[36:39]
	v_mfma_f32_16x16x32_bf16 v[32:35], v[154:157], v[202:205], v[32:35]
	s_setprio 0
	s_setprio 1
	v_mfma_f32_16x16x32_bf16 v[28:31], v[158:161], v[174:177], v[28:31]
	v_mfma_f32_16x16x32_bf16 v[24:27], v[166:169], v[174:177], v[24:27]
	v_mfma_f32_16x16x32_bf16 v[20:23], v[158:161], v[182:185], v[20:23]
	v_mfma_f32_16x16x32_bf16 v[16:19], v[166:169], v[182:185], v[16:19]
	v_mfma_f32_16x16x32_bf16 v[12:15], v[158:161], v[190:193], v[12:15]
	v_mfma_f32_16x16x32_bf16 v[8:11], v[166:169], v[190:193], v[8:11]
	v_mfma_f32_16x16x32_bf16 v[4:7], v[158:161], v[198:201], v[4:7]
	v_mfma_f32_16x16x32_bf16 v[0:3], v[166:169], v[198:201], v[0:3]
	v_mfma_f32_16x16x32_bf16 v[28:31], v[162:165], v[178:181], v[28:31]
	v_mfma_f32_16x16x32_bf16 v[24:27], v[170:173], v[178:181], v[24:27]
	v_mfma_f32_16x16x32_bf16 v[20:23], v[162:165], v[186:189], v[20:23]
	v_mfma_f32_16x16x32_bf16 v[16:19], v[170:173], v[186:189], v[16:19]
	v_mfma_f32_16x16x32_bf16 v[12:15], v[162:165], v[194:197], v[12:15]
	v_mfma_f32_16x16x32_bf16 v[8:11], v[170:173], v[194:197], v[8:11]
	v_mfma_f32_16x16x32_bf16 v[4:7], v[162:165], v[202:205], v[4:7]
	v_mfma_f32_16x16x32_bf16 v[0:3], v[170:173], v[202:205], v[0:3]
	s_setprio 0
	s_barrier
	s_add_i32 s86, 0, 0x18000
	s_add_i32 s87, 0, 0x1c000
	v_add_u32_e32 v154, s86, v214
	v_add_u32_e32 v230, s86, v233
	v_add_u32_e32 v170, s87, v214
	v_add_u32_e32 v231, s87, v233
	ds_read_b128 v[142:145], v154
	ds_read_b128 v[146:149], v230
	ds_read_b128 v[150:153], v154 offset:2048
	ds_read_b128 v[154:157], v230 offset:2048
	ds_read_b128 v[158:161], v170
	ds_read_b128 v[162:165], v231
	ds_read_b128 v[166:169], v170 offset:2048
	ds_read_b128 v[170:173], v231 offset:2048
	s_add_u32 s48, s48, 0x100000
	s_addc_u32 s49, s49, 0
	s_mov_b32 m0, s57
	v_lshl_add_u64 v[220:221], s[48:49], 0, v[130:131]
	ds_read_b128 v[174:177], v216 offset:32768
	ds_read_b128 v[178:181], v232 offset:32768
	ds_read_b128 v[182:185], v216 offset:34816
	ds_read_b128 v[186:189], v232 offset:34816
	ds_read_b128 v[190:193], v216 offset:36864
	ds_read_b128 v[194:197], v232 offset:36864
	ds_read_b128 v[198:201], v216 offset:38912
	ds_read_b128 v[202:205], v232 offset:38912
	global_load_lds_dwordx4 v[220:221], off
	v_lshl_add_u64 v[220:221], s[48:49], 0, v[128:129]
	s_mov_b32 m0, s58
	s_nop 0
	global_load_lds_dwordx4 v[220:221], off
	s_waitcnt vmcnt(8)
	s_waitcnt lgkmcnt(0)
	s_barrier
	s_setprio 1
	s_waitcnt lgkmcnt(0)
	v_mfma_f32_16x16x32_bf16 v[124:127], v[142:145], v[174:177], v[124:127]
	v_mfma_f32_16x16x32_bf16 v[120:123], v[150:153], v[174:177], v[120:123]
	v_mfma_f32_16x16x32_bf16 v[116:119], v[142:145], v[182:185], v[116:119]
	v_mfma_f32_16x16x32_bf16 v[112:115], v[150:153], v[182:185], v[112:115]
	v_mfma_f32_16x16x32_bf16 v[108:111], v[142:145], v[190:193], v[108:111]
	v_mfma_f32_16x16x32_bf16 v[104:107], v[150:153], v[190:193], v[104:107]
	v_mfma_f32_16x16x32_bf16 v[100:103], v[142:145], v[198:201], v[100:103]
	v_mfma_f32_16x16x32_bf16 v[96:99], v[150:153], v[198:201], v[96:99]
	v_mfma_f32_16x16x32_bf16 v[124:127], v[146:149], v[178:181], v[124:127]
	v_mfma_f32_16x16x32_bf16 v[120:123], v[154:157], v[178:181], v[120:123]
	v_mfma_f32_16x16x32_bf16 v[116:119], v[146:149], v[186:189], v[116:119]
	v_mfma_f32_16x16x32_bf16 v[112:115], v[154:157], v[186:189], v[112:115]
	v_mfma_f32_16x16x32_bf16 v[108:111], v[146:149], v[194:197], v[108:111]
	v_mfma_f32_16x16x32_bf16 v[104:107], v[154:157], v[194:197], v[104:107]
	v_mfma_f32_16x16x32_bf16 v[100:103], v[146:149], v[202:205], v[100:103]
	v_mfma_f32_16x16x32_bf16 v[96:99], v[154:157], v[202:205], v[96:99]
	s_setprio 0
	s_setprio 1
	v_mfma_f32_16x16x32_bf16 v[92:95], v[158:161], v[174:177], v[92:95]
	v_mfma_f32_16x16x32_bf16 v[88:91], v[166:169], v[174:177], v[88:91]
	v_mfma_f32_16x16x32_bf16 v[84:87], v[158:161], v[182:185], v[84:87]
	v_mfma_f32_16x16x32_bf16 v[80:83], v[166:169], v[182:185], v[80:83]
	v_mfma_f32_16x16x32_bf16 v[76:79], v[158:161], v[190:193], v[76:79]
	v_mfma_f32_16x16x32_bf16 v[72:75], v[166:169], v[190:193], v[72:75]
	v_mfma_f32_16x16x32_bf16 v[68:71], v[158:161], v[198:201], v[68:71]
	v_mfma_f32_16x16x32_bf16 v[64:67], v[166:169], v[198:201], v[64:67]
	v_mfma_f32_16x16x32_bf16 v[92:95], v[162:165], v[178:181], v[92:95]
	v_mfma_f32_16x16x32_bf16 v[88:91], v[170:173], v[178:181], v[88:91]
	v_mfma_f32_16x16x32_bf16 v[84:87], v[162:165], v[186:189], v[84:87]
	v_mfma_f32_16x16x32_bf16 v[80:83], v[170:173], v[186:189], v[80:83]
	v_mfma_f32_16x16x32_bf16 v[76:79], v[162:165], v[194:197], v[76:79]
	v_mfma_f32_16x16x32_bf16 v[72:75], v[170:173], v[194:197], v[72:75]
	v_mfma_f32_16x16x32_bf16 v[68:71], v[162:165], v[202:205], v[68:71]
	v_mfma_f32_16x16x32_bf16 v[64:67], v[170:173], v[202:205], v[64:67]
	s_setprio 0
	s_barrier
; template <class Epi, class Sched, bool FP8 = false>
; __device__ __forceinline__ void gemm_phase(LAS unsigned char* lds, const Gemm g, const Sched& S, const Epi& E, const int tid) {
;     ...
;         for (int t = 0; t < nt; t += 2) PG8_KBODY(t);
	s_add_i32 s48, s86, s54
	v_lshl_add_u64 v[206:207], v[206:207], 0, s[14:15]
	s_mov_b32 m0, s48
	ds_read_b128 v[174:177], v216 offset:49152
	ds_read_b128 v[178:181], v232 offset:49152
	ds_read_b128 v[182:185], v216 offset:51200
	ds_read_b128 v[186:189], v232 offset:51200
	ds_read_b128 v[190:193], v216 offset:53248
	ds_read_b128 v[194:197], v232 offset:53248
	ds_read_b128 v[198:201], v216 offset:55296
	ds_read_b128 v[202:205], v232 offset:55296
	global_load_lds_dwordx4 v[206:207], off
	s_add_i32 m0, s48, 0x2000
	s_add_u32 s46, s46, 0x100080
	v_lshl_add_u64 v[206:207], v[208:209], 0, s[14:15]
	s_addc_u32 s47, s47, 0
	s_add_i32 s48, s87, s54
	global_load_lds_dwordx4 v[206:207], off
	v_lshl_add_u64 v[206:207], s[46:47], 0, v[130:131]
	s_mov_b32 m0, s48
	s_nop 0
	global_load_lds_dwordx4 v[206:207], off
	v_lshl_add_u64 v[206:207], s[46:47], 0, v[128:129]
	s_add_i32 m0, s48, 0x2000
	s_nop 0
	global_load_lds_dwordx4 v[206:207], off
	v_lshl_add_u64 v[206:207], v[210:211], 0, s[14:15]
	s_mov_b32 m0, s66
	s_nop 0
	global_load_lds_dwordx4 v[206:207], off
	v_lshl_add_u64 v[206:207], v[218:219], 0, s[14:15]
	s_mov_b32 m0, s68
	s_nop 0
	global_load_lds_dwordx4 v[206:207], off
	s_waitcnt vmcnt(8)
	s_waitcnt lgkmcnt(0)
	s_barrier
	s_setprio 1
	s_waitcnt lgkmcnt(0)
	v_mfma_f32_16x16x32_bf16 v[60:63], v[142:145], v[174:177], v[60:63]
	v_mfma_f32_16x16x32_bf16 v[56:59], v[150:153], v[174:177], v[56:59]
	v_mfma_f32_16x16x32_bf16 v[52:55], v[142:145], v[182:185], v[52:55]
	v_mfma_f32_16x16x32_bf16 v[48:51], v[150:153], v[182:185], v[48:51]
	v_mfma_f32_16x16x32_bf16 v[44:47], v[142:145], v[190:193], v[44:47]
	v_mfma_f32_16x16x32_bf16 v[40:43], v[150:153], v[190:193], v[40:43]
	v_mfma_f32_16x16x32_bf16 v[36:39], v[142:145], v[198:201], v[36:39]
	v_mfma_f32_16x16x32_bf16 v[32:35], v[150:153], v[198:201], v[32:35]
	v_mfma_f32_16x16x32_bf16 v[60:63], v[146:149], v[178:181], v[60:63]
	v_mfma_f32_16x16x32_bf16 v[56:59], v[154:157], v[178:181], v[56:59]
	v_mfma_f32_16x16x32_bf16 v[52:55], v[146:149], v[186:189], v[52:55]
	v_mfma_f32_16x16x32_bf16 v[48:51], v[154:157], v[186:189], v[48:51]
	v_mfma_f32_16x16x32_bf16 v[44:47], v[146:149], v[194:197], v[44:47]
	v_mfma_f32_16x16x32_bf16 v[40:43], v[154:157], v[194:197], v[40:43]
	v_mfma_f32_16x16x32_bf16 v[36:39], v[146:149], v[202:205], v[36:39]
	v_mfma_f32_16x16x32_bf16 v[32:35], v[154:157], v[202:205], v[32:35]
	s_setprio 0
	s_setprio 1
	v_mfma_f32_16x16x32_bf16 v[28:31], v[158:161], v[174:177], v[28:31]
	v_mfma_f32_16x16x32_bf16 v[24:27], v[166:169], v[174:177], v[24:27]
	v_mfma_f32_16x16x32_bf16 v[20:23], v[158:161], v[182:185], v[20:23]
	v_mfma_f32_16x16x32_bf16 v[16:19], v[166:169], v[182:185], v[16:19]
	v_mfma_f32_16x16x32_bf16 v[12:15], v[158:161], v[190:193], v[12:15]
	v_mfma_f32_16x16x32_bf16 v[8:11], v[166:169], v[190:193], v[8:11]
	v_mfma_f32_16x16x32_bf16 v[4:7], v[158:161], v[198:201], v[4:7]
	v_mfma_f32_16x16x32_bf16 v[0:3], v[166:169], v[198:201], v[0:3]
	v_mfma_f32_16x16x32_bf16 v[28:31], v[162:165], v[178:181], v[28:31]
	v_mfma_f32_16x16x32_bf16 v[24:27], v[170:173], v[178:181], v[24:27]
	v_mfma_f32_16x16x32_bf16 v[20:23], v[162:165], v[186:189], v[20:23]
	v_mfma_f32_16x16x32_bf16 v[16:19], v[170:173], v[186:189], v[16:19]
	v_mfma_f32_16x16x32_bf16 v[12:15], v[162:165], v[194:197], v[12:15]
	v_mfma_f32_16x16x32_bf16 v[8:11], v[170:173], v[194:197], v[8:11]
	v_mfma_f32_16x16x32_bf16 v[4:7], v[162:165], v[202:205], v[4:7]
	v_mfma_f32_16x16x32_bf16 v[0:3], v[170:173], v[202:205], v[0:3]
	s_setprio 0
	s_add_i32 s85, s85, 2
	s_add_u32 s4, s4, 0x100
	s_addc_u32 s5, s5, 0
	s_add_u32 s83, s83, 0x100
	s_addc_u32 s84, s84, 0
	s_cmp_gt_u32 s85, 29
	s_barrier
	s_cbranch_scc0 .LBB0_471
	s_and_b64 vcc, exec, s[16:17]
	s_cbranch_vccz .LBB0_474
	s_barrier

.LBB0_560:
	ds_read_b128 v[128:131], v203
	ds_read_b128 v[132:135], v234
	ds_read_b128 v[136:139], v203 offset:2048
	ds_read_b128 v[140:143], v234 offset:2048
	ds_read_b128 v[144:147], v204
	ds_read_b128 v[148:151], v235
	ds_read_b128 v[152:155], v204 offset:2048
	ds_read_b128 v[156:159], v235 offset:2048
	s_add_u32 s42, s38, 0xfff00080
	s_addc_u32 s43, s39, -1
	s_cmp_eq_u32 s64, 60
	s_cselect_b32 s45, s29, s43
	s_cselect_b32 s44, s41, s42
	s_cselect_b32 s43, s27, s63
	s_cselect_b32 s42, s61, s62
	v_lshl_add_u64 v[212:213], s[38:39], 0, v[180:181]
	s_add_i32 m0, s17, 0xc000
	ds_read_b128 v[160:163], v205
	ds_read_b128 v[164:167], v232
	ds_read_b128 v[168:171], v205 offset:2048
	ds_read_b128 v[172:175], v232 offset:2048
	ds_read_b128 v[188:191], v205 offset:4096
	ds_read_b128 v[192:195], v232 offset:4096
	ds_read_b128 v[196:199], v205 offset:6144
	ds_read_b128 v[208:211], v232 offset:6144
	global_load_lds_dwordx4 v[212:213], off
	v_lshl_add_u64 v[212:213], s[38:39], 0, v[182:183]
	s_add_i32 m0, s17, 0xe000
	s_nop 0
	global_load_lds_dwordx4 v[212:213], off
	s_waitcnt vmcnt(8)
	s_waitcnt lgkmcnt(0)
	s_barrier
	s_setprio 1
	s_waitcnt lgkmcnt(0)
	v_mfma_f32_16x16x32_bf16 v[124:127], v[128:131], v[160:163], v[124:127]
	v_mfma_f32_16x16x32_bf16 v[120:123], v[136:139], v[160:163], v[120:123]
	v_mfma_f32_16x16x32_bf16 v[108:111], v[128:131], v[168:171], v[108:111]
	v_mfma_f32_16x16x32_bf16 v[104:107], v[136:139], v[168:171], v[104:107]
	v_mfma_f32_16x16x32_bf16 v[92:95], v[128:131], v[188:191], v[92:95]
	v_mfma_f32_16x16x32_bf16 v[88:91], v[136:139], v[188:191], v[88:91]
	v_mfma_f32_16x16x32_bf16 v[76:79], v[128:131], v[196:199], v[76:79]
	v_mfma_f32_16x16x32_bf16 v[72:75], v[136:139], v[196:199], v[72:75]
	v_mfma_f32_16x16x32_bf16 v[124:127], v[132:135], v[164:167], v[124:127]
	v_mfma_f32_16x16x32_bf16 v[120:123], v[140:143], v[164:167], v[120:123]
	v_mfma_f32_16x16x32_bf16 v[108:111], v[132:135], v[172:175], v[108:111]
	v_mfma_f32_16x16x32_bf16 v[104:107], v[140:143], v[172:175], v[104:107]
	v_mfma_f32_16x16x32_bf16 v[92:95], v[132:135], v[192:195], v[92:95]
	v_mfma_f32_16x16x32_bf16 v[88:91], v[140:143], v[192:195], v[88:91]
	v_mfma_f32_16x16x32_bf16 v[76:79], v[132:135], v[208:211], v[76:79]
	v_mfma_f32_16x16x32_bf16 v[72:75], v[140:143], v[208:211], v[72:75]
	s_setprio 0
	s_setprio 1
	v_mfma_f32_16x16x32_bf16 v[116:119], v[144:147], v[160:163], v[116:119]
	v_mfma_f32_16x16x32_bf16 v[112:115], v[152:155], v[160:163], v[112:115]
	v_mfma_f32_16x16x32_bf16 v[100:103], v[144:147], v[168:171], v[100:103]
	v_mfma_f32_16x16x32_bf16 v[96:99], v[152:155], v[168:171], v[96:99]
	v_mfma_f32_16x16x32_bf16 v[84:87], v[144:147], v[188:191], v[84:87]
	v_mfma_f32_16x16x32_bf16 v[80:83], v[152:155], v[188:191], v[80:83]
	v_mfma_f32_16x16x32_bf16 v[68:71], v[144:147], v[196:199], v[68:71]
	v_mfma_f32_16x16x32_bf16 v[64:67], v[152:155], v[196:199], v[64:67]
	v_mfma_f32_16x16x32_bf16 v[116:119], v[148:151], v[164:167], v[116:119]
	v_mfma_f32_16x16x32_bf16 v[112:115], v[156:159], v[164:167], v[112:115]
	v_mfma_f32_16x16x32_bf16 v[100:103], v[148:151], v[172:175], v[100:103]
	v_mfma_f32_16x16x32_bf16 v[96:99], v[156:159], v[172:175], v[96:99]
	v_mfma_f32_16x16x32_bf16 v[84:87], v[148:151], v[192:195], v[84:87]
	v_mfma_f32_16x16x32_bf16 v[80:83], v[156:159], v[192:195], v[80:83]
	v_mfma_f32_16x16x32_bf16 v[68:71], v[148:151], v[208:211], v[68:71]
	v_mfma_f32_16x16x32_bf16 v[64:67], v[156:159], v[208:211], v[64:67]
	s_setprio 0
	s_barrier
	s_add_i32 s65, s59, s52
	v_lshl_add_u64 v[212:213], s[42:43], 0, v[176:177]
	s_mov_b32 m0, s65
	ds_read_b128 v[160:163], v205 offset:16384
	ds_read_b128 v[164:167], v232 offset:16384
	ds_read_b128 v[168:171], v205 offset:18432
	ds_read_b128 v[172:175], v232 offset:18432
	ds_read_b128 v[188:191], v205 offset:20480
	ds_read_b128 v[192:195], v232 offset:20480
	ds_read_b128 v[196:199], v205 offset:22528
	ds_read_b128 v[208:211], v232 offset:22528
	global_load_lds_dwordx4 v[212:213], off
	s_add_i32 m0, s65, 0x2000
	s_add_u32 s66, s42, 0x100000
	v_lshl_add_u64 v[214:215], s[42:43], 0, v[178:179]
	s_addc_u32 s67, s43, 0
	s_add_i32 s65, s60, s52
	global_load_lds_dwordx4 v[214:215], off
	v_lshl_add_u64 v[216:217], s[66:67], 0, v[176:177]
	s_mov_b32 m0, s65
	v_lshl_add_u64 v[218:219], s[44:45], 0, v[178:179]
	global_load_lds_dwordx4 v[216:217], off
	v_lshl_add_u64 v[216:217], s[66:67], 0, v[178:179]
	s_add_i32 m0, s65, 0x2000
	s_nop 0
	global_load_lds_dwordx4 v[216:217], off
	v_lshl_add_u64 v[216:217], s[44:45], 0, v[176:177]
	s_mov_b32 m0, s17
	s_nop 0
	global_load_lds_dwordx4 v[216:217], off
	s_mov_b32 m0, s53
	s_nop 0
	global_load_lds_dwordx4 v[218:219], off
	s_waitcnt vmcnt(8)
	s_waitcnt lgkmcnt(0)
	s_barrier
	s_setprio 1
	s_waitcnt lgkmcnt(0)
	v_mfma_f32_16x16x32_bf16 v[60:63], v[128:131], v[160:163], v[60:63]
	v_mfma_f32_16x16x32_bf16 v[56:59], v[136:139], v[160:163], v[56:59]
	v_mfma_f32_16x16x32_bf16 v[44:47], v[128:131], v[168:171], v[44:47]
	v_mfma_f32_16x16x32_bf16 v[40:43], v[136:139], v[168:171], v[40:43]
	v_mfma_f32_16x16x32_bf16 v[28:31], v[128:131], v[188:191], v[28:31]
	v_mfma_f32_16x16x32_bf16 v[24:27], v[136:139], v[188:191], v[24:27]
	v_mfma_f32_16x16x32_bf16 v[12:15], v[128:131], v[196:199], v[12:15]
	v_mfma_f32_16x16x32_bf16 v[8:11], v[136:139], v[196:199], v[8:11]
	v_mfma_f32_16x16x32_bf16 v[60:63], v[132:135], v[164:167], v[60:63]
	v_mfma_f32_16x16x32_bf16 v[56:59], v[140:143], v[164:167], v[56:59]
	v_mfma_f32_16x16x32_bf16 v[44:47], v[132:135], v[172:175], v[44:47]
	v_mfma_f32_16x16x32_bf16 v[40:43], v[140:143], v[172:175], v[40:43]
	v_mfma_f32_16x16x32_bf16 v[28:31], v[132:135], v[192:195], v[28:31]
	v_mfma_f32_16x16x32_bf16 v[24:27], v[140:143], v[192:195], v[24:27]
	v_mfma_f32_16x16x32_bf16 v[12:15], v[132:135], v[208:211], v[12:15]
	v_mfma_f32_16x16x32_bf16 v[8:11], v[140:143], v[208:211], v[8:11]
	s_setprio 0
	s_setprio 1
	v_mfma_f32_16x16x32_bf16 v[52:55], v[144:147], v[160:163], v[52:55]
	v_mfma_f32_16x16x32_bf16 v[48:51], v[152:155], v[160:163], v[48:51]
	v_mfma_f32_16x16x32_bf16 v[36:39], v[144:147], v[168:171], v[36:39]
	v_mfma_f32_16x16x32_bf16 v[32:35], v[152:155], v[168:171], v[32:35]
	v_mfma_f32_16x16x32_bf16 v[20:23], v[144:147], v[188:191], v[20:23]
	v_mfma_f32_16x16x32_bf16 v[16:19], v[152:155], v[188:191], v[16:19]
	v_mfma_f32_16x16x32_bf16 v[4:7], v[144:147], v[196:199], v[4:7]
	v_mfma_f32_16x16x32_bf16 v[0:3], v[152:155], v[196:199], v[0:3]
	v_mfma_f32_16x16x32_bf16 v[52:55], v[148:151], v[164:167], v[52:55]
	v_mfma_f32_16x16x32_bf16 v[48:51], v[156:159], v[164:167], v[48:51]
	v_mfma_f32_16x16x32_bf16 v[36:39], v[148:151], v[172:175], v[36:39]
	v_mfma_f32_16x16x32_bf16 v[32:35], v[156:159], v[172:175], v[32:35]
	v_mfma_f32_16x16x32_bf16 v[20:23], v[148:151], v[192:195], v[20:23]
	v_mfma_f32_16x16x32_bf16 v[16:19], v[156:159], v[192:195], v[16:19]
	v_mfma_f32_16x16x32_bf16 v[4:7], v[148:151], v[208:211], v[4:7]
	v_mfma_f32_16x16x32_bf16 v[0:3], v[156:159], v[208:211], v[0:3]
	s_setprio 0
	s_barrier
	s_add_i32 s65, 0, 0x18000
	s_add_i32 s66, 0, 0x1c000
	v_add_u32_e32 v140, s65, v201
	v_add_u32_e32 v230, s65, v233
	v_add_u32_e32 v156, s66, v201
	v_add_u32_e32 v231, s66, v233
	ds_read_b128 v[128:131], v140
	ds_read_b128 v[132:135], v230
	ds_read_b128 v[136:139], v140 offset:2048
	ds_read_b128 v[140:143], v230 offset:2048
	ds_read_b128 v[144:147], v156
	ds_read_b128 v[148:151], v231
	ds_read_b128 v[152:155], v156 offset:2048
	ds_read_b128 v[156:159], v231 offset:2048
	s_add_u32 s44, s44, 0x100000
	s_addc_u32 s45, s45, 0
	s_mov_b32 m0, s54
	v_lshl_add_u64 v[220:221], s[44:45], 0, v[176:177]
	ds_read_b128 v[160:163], v205 offset:32768
	ds_read_b128 v[164:167], v232 offset:32768
	ds_read_b128 v[168:171], v205 offset:34816
	ds_read_b128 v[172:175], v232 offset:34816
	ds_read_b128 v[188:191], v205 offset:36864
	ds_read_b128 v[192:195], v232 offset:36864
	ds_read_b128 v[196:199], v205 offset:38912
	ds_read_b128 v[208:211], v232 offset:38912
	global_load_lds_dwordx4 v[220:221], off
	v_lshl_add_u64 v[220:221], s[44:45], 0, v[178:179]
	s_mov_b32 m0, s55
	s_nop 0
	global_load_lds_dwordx4 v[220:221], off
	s_waitcnt vmcnt(8)
	s_waitcnt lgkmcnt(0)
	s_barrier
	s_setprio 1
	s_waitcnt lgkmcnt(0)
	v_mfma_f32_16x16x32_bf16 v[124:127], v[128:131], v[160:163], v[124:127]
	v_mfma_f32_16x16x32_bf16 v[120:123], v[136:139], v[160:163], v[120:123]
	v_mfma_f32_16x16x32_bf16 v[108:111], v[128:131], v[168:171], v[108:111]
	v_mfma_f32_16x16x32_bf16 v[104:107], v[136:139], v[168:171], v[104:107]
	v_mfma_f32_16x16x32_bf16 v[92:95], v[128:131], v[188:191], v[92:95]
	v_mfma_f32_16x16x32_bf16 v[88:91], v[136:139], v[188:191], v[88:91]
	v_mfma_f32_16x16x32_bf16 v[76:79], v[128:131], v[196:199], v[76:79]
	v_mfma_f32_16x16x32_bf16 v[72:75], v[136:139], v[196:199], v[72:75]
	v_mfma_f32_16x16x32_bf16 v[124:127], v[132:135], v[164:167], v[124:127]
	v_mfma_f32_16x16x32_bf16 v[120:123], v[140:143], v[164:167], v[120:123]
	v_mfma_f32_16x16x32_bf16 v[108:111], v[132:135], v[172:175], v[108:111]
	v_mfma_f32_16x16x32_bf16 v[104:107], v[140:143], v[172:175], v[104:107]
	v_mfma_f32_16x16x32_bf16 v[92:95], v[132:135], v[192:195], v[92:95]
	v_mfma_f32_16x16x32_bf16 v[88:91], v[140:143], v[192:195], v[88:91]
	v_mfma_f32_16x16x32_bf16 v[76:79], v[132:135], v[208:211], v[76:79]
	v_mfma_f32_16x16x32_bf16 v[72:75], v[140:143], v[208:211], v[72:75]
	s_setprio 0
	s_setprio 1
	v_mfma_f32_16x16x32_bf16 v[116:119], v[144:147], v[160:163], v[116:119]
	v_mfma_f32_16x16x32_bf16 v[112:115], v[152:155], v[160:163], v[112:115]
	v_mfma_f32_16x16x32_bf16 v[100:103], v[144:147], v[168:171], v[100:103]
	v_mfma_f32_16x16x32_bf16 v[96:99], v[152:155], v[168:171], v[96:99]
	v_mfma_f32_16x16x32_bf16 v[84:87], v[144:147], v[188:191], v[84:87]
	v_mfma_f32_16x16x32_bf16 v[80:83], v[152:155], v[188:191], v[80:83]
	v_mfma_f32_16x16x32_bf16 v[68:71], v[144:147], v[196:199], v[68:71]
	v_mfma_f32_16x16x32_bf16 v[64:67], v[152:155], v[196:199], v[64:67]
	v_mfma_f32_16x16x32_bf16 v[116:119], v[148:151], v[164:167], v[116:119]
	v_mfma_f32_16x16x32_bf16 v[112:115], v[156:159], v[164:167], v[112:115]
	v_mfma_f32_16x16x32_bf16 v[100:103], v[148:151], v[172:175], v[100:103]
	v_mfma_f32_16x16x32_bf16 v[96:99], v[156:159], v[172:175], v[96:99]
	v_mfma_f32_16x16x32_bf16 v[84:87], v[148:151], v[192:195], v[84:87]
	v_mfma_f32_16x16x32_bf16 v[80:83], v[156:159], v[192:195], v[80:83]
	v_mfma_f32_16x16x32_bf16 v[68:71], v[148:151], v[208:211], v[68:71]
	v_mfma_f32_16x16x32_bf16 v[64:67], v[156:159], v[208:211], v[64:67]
	s_setprio 0
	s_barrier
; template <class Epi, class Sched, bool FP8 = false>
; __device__ __forceinline__ void gemm_phase(LAS unsigned char* lds, const Gemm g, const Sched& S, const Epi& E, const int tid) {
;     ...
;         for (int t = 0; t < nt; t += 2) PG8_KBODY(t);
	s_add_i32 s44, s65, s52
	v_lshl_add_u64 v[212:213], v[212:213], 0, s[22:23]
	s_mov_b32 m0, s44
	ds_read_b128 v[160:163], v205 offset:49152
	ds_read_b128 v[164:167], v232 offset:49152
	ds_read_b128 v[168:171], v205 offset:51200
	ds_read_b128 v[172:175], v232 offset:51200
	ds_read_b128 v[188:191], v205 offset:53248
	ds_read_b128 v[192:195], v232 offset:53248
	ds_read_b128 v[196:199], v205 offset:55296
	ds_read_b128 v[208:211], v232 offset:55296
	global_load_lds_dwordx4 v[212:213], off
	s_add_i32 m0, s44, 0x2000
	s_add_u32 s42, s42, 0x100080
	v_lshl_add_u64 v[212:213], v[214:215], 0, s[22:23]
	s_addc_u32 s43, s43, 0
	s_add_i32 s44, s66, s52
	global_load_lds_dwordx4 v[212:213], off
	v_lshl_add_u64 v[212:213], s[42:43], 0, v[176:177]
	s_mov_b32 m0, s44
	s_nop 0
	global_load_lds_dwordx4 v[212:213], off
	v_lshl_add_u64 v[212:213], s[42:43], 0, v[178:179]
	s_add_i32 m0, s44, 0x2000
	s_nop 0
	global_load_lds_dwordx4 v[212:213], off
	v_lshl_add_u64 v[212:213], v[216:217], 0, s[22:23]
	s_mov_b32 m0, s57
	s_nop 0
	global_load_lds_dwordx4 v[212:213], off
	v_lshl_add_u64 v[212:213], v[218:219], 0, s[22:23]
	s_mov_b32 m0, s58
	s_nop 0
	global_load_lds_dwordx4 v[212:213], off
	s_waitcnt vmcnt(8)
	s_waitcnt lgkmcnt(0)
	s_barrier
	s_setprio 1
	s_waitcnt lgkmcnt(0)
	v_mfma_f32_16x16x32_bf16 v[60:63], v[128:131], v[160:163], v[60:63]
	v_mfma_f32_16x16x32_bf16 v[56:59], v[136:139], v[160:163], v[56:59]
	v_mfma_f32_16x16x32_bf16 v[44:47], v[128:131], v[168:171], v[44:47]
	v_mfma_f32_16x16x32_bf16 v[40:43], v[136:139], v[168:171], v[40:43]
	v_mfma_f32_16x16x32_bf16 v[28:31], v[128:131], v[188:191], v[28:31]
	v_mfma_f32_16x16x32_bf16 v[24:27], v[136:139], v[188:191], v[24:27]
	v_mfma_f32_16x16x32_bf16 v[12:15], v[128:131], v[196:199], v[12:15]
	v_mfma_f32_16x16x32_bf16 v[8:11], v[136:139], v[196:199], v[8:11]
	v_mfma_f32_16x16x32_bf16 v[60:63], v[132:135], v[164:167], v[60:63]
	v_mfma_f32_16x16x32_bf16 v[56:59], v[140:143], v[164:167], v[56:59]
	v_mfma_f32_16x16x32_bf16 v[44:47], v[132:135], v[172:175], v[44:47]
	v_mfma_f32_16x16x32_bf16 v[40:43], v[140:143], v[172:175], v[40:43]
	v_mfma_f32_16x16x32_bf16 v[28:31], v[132:135], v[192:195], v[28:31]
	v_mfma_f32_16x16x32_bf16 v[24:27], v[140:143], v[192:195], v[24:27]
	v_mfma_f32_16x16x32_bf16 v[12:15], v[132:135], v[208:211], v[12:15]
	v_mfma_f32_16x16x32_bf16 v[8:11], v[140:143], v[208:211], v[8:11]
	s_setprio 0
	s_setprio 1
	v_mfma_f32_16x16x32_bf16 v[52:55], v[144:147], v[160:163], v[52:55]
	v_mfma_f32_16x16x32_bf16 v[48:51], v[152:155], v[160:163], v[48:51]
	v_mfma_f32_16x16x32_bf16 v[36:39], v[144:147], v[168:171], v[36:39]
	v_mfma_f32_16x16x32_bf16 v[32:35], v[152:155], v[168:171], v[32:35]
	v_mfma_f32_16x16x32_bf16 v[20:23], v[144:147], v[188:191], v[20:23]
	v_mfma_f32_16x16x32_bf16 v[16:19], v[152:155], v[188:191], v[16:19]
	v_mfma_f32_16x16x32_bf16 v[4:7], v[144:147], v[196:199], v[4:7]
	v_mfma_f32_16x16x32_bf16 v[0:3], v[152:155], v[196:199], v[0:3]
	v_mfma_f32_16x16x32_bf16 v[52:55], v[148:151], v[164:167], v[52:55]
	v_mfma_f32_16x16x32_bf16 v[48:51], v[156:159], v[164:167], v[48:51]
	v_mfma_f32_16x16x32_bf16 v[36:39], v[148:151], v[172:175], v[36:39]
	v_mfma_f32_16x16x32_bf16 v[32:35], v[156:159], v[172:175], v[32:35]
	v_mfma_f32_16x16x32_bf16 v[20:23], v[148:151], v[192:195], v[20:23]
	v_mfma_f32_16x16x32_bf16 v[16:19], v[156:159], v[192:195], v[16:19]
	v_mfma_f32_16x16x32_bf16 v[4:7], v[148:151], v[208:211], v[4:7]
	v_mfma_f32_16x16x32_bf16 v[0:3], v[156:159], v[208:211], v[0:3]
	s_setprio 0
	s_add_i32 s64, s64, 2
	s_add_u32 s38, s38, 0x100
	s_addc_u32 s39, s39, 0
	s_add_u32 s62, s62, 0x100
	s_addc_u32 s63, s63, 0
	s_cmp_gt_u32 s64, 61
	s_barrier
	s_cbranch_scc0 .LBB0_560
	s_and_b64 vcc, exec, s[24:25]
	s_cbranch_vccz .LBB0_563
	s_barrier
